# prep: next unit conv rows L2-warmed during step 4; first-barrier census: 16 counter loads issued together
# speedup vs baseline: 1.0355x; 1.0066x over previous
.Lgs_88:
	s_mov_b64 s[10:11], -1
	s_waitcnt lgkmcnt(0)
	global_load_dword v2, v157, s[50:51] offset:0 sc1
	global_load_dword v0, v157, s[50:51] offset:256 sc1
	global_load_dword v1, v157, s[50:51] offset:512 sc1
	global_load_dword v3, v157, s[50:51] offset:768 sc1
	global_load_dword v4, v157, s[50:51] offset:1024 sc1
	global_load_dword v5, v157, s[50:51] offset:1280 sc1
	global_load_dword v6, v157, s[50:51] offset:1536 sc1
	global_load_dword v7, v157, s[50:51] offset:1792 sc1
	global_load_dword v8, v157, s[50:51] offset:2048 sc1
	global_load_dword v9, v157, s[50:51] offset:2304 sc1
	global_load_dword v10, v157, s[50:51] offset:2560 sc1
	global_load_dword v11, v157, s[50:51] offset:2816 sc1
	global_load_dword v12, v157, s[50:51] offset:3072 sc1
	global_load_dword v13, v157, s[50:51] offset:3328 sc1
	global_load_dword v14, v157, s[50:51] offset:3584 sc1
	global_load_dword v15, v157, s[50:51] offset:3840 sc1
	s_mov_b64 s[8:9], -1
	s_waitcnt vmcnt(0)
	v_add3_u32 v16, v0, v2, v1
	v_add3_u32 v16, v16, v3, v4
	v_add3_u32 v16, v16, v5, v6
	v_add3_u32 v16, v16, v7, v8
	v_add3_u32 v16, v16, v9, v10
	v_add3_u32 v16, v16, v11, v12
	v_add3_u32 v16, v16, v13, v14
	v_add_u32_e32 v16, v16, v15
	v_cmp_eq_u32_e32 vcc, s62, v16
	s_cbranch_vccnz .Lgs_87
	s_and_b32 s8, s14, 0xff
	s_cmp_eq_u32 s8, 0
	s_mov_b64 s[8:9], -1
	s_mov_b64 s[12:13], -1
	s_sleep 1
	s_cbranch_scc0 .Lgs_92
	global_load_dword v16, v157, s[88:89] sc1
	s_waitcnt vmcnt(0)
	v_cmp_eq_u32_e32 vcc, 0, v16
	s_cbranch_vccnz .Lgs_94
	s_mov_b64 s[12:13], 0

.LBB0_543:
	s_waitcnt lgkmcnt(0)
	s_barrier
	s_cmpk_ge_i32 s10, 0x300
	s_cbranch_scc1 .Lprep_pf_skip
	s_add_u32 s0, s14, s6
	v_readlane_b32 s1, v254, 1
	s_nop 1
	s_addc_u32 s1, s15, s1
	s_add_u32 s0, s0, 0x1000
	s_addc_u32 s1, s1, 0
	s_mulk_i32 s1, 0x1e00
	s_mul_hi_u32 s16, s0, 0x1e00
	s_add_i32 s1, s16, s1
	s_mulk_i32 s0, 0x1e00
	s_add_u32 s0, s20, s0
	s_addc_u32 s1, s21, s1
	v_or_b32_e32 v243, s53, v8
	v_lshlrev_b32_e32 v243, 1, v243
	global_load_dword v242, v243, s[0:1] offset:1536
	global_load_dword v242, v243, s[0:1] offset:2560
	global_load_dword v242, v243, s[0:1] offset:3584
	s_add_u32 s0, s0, 0x1e00
	s_addc_u32 s1, s1, 0
	global_load_dword v242, v243, s[0:1] offset:1536
	global_load_dword v242, v243, s[0:1] offset:2560
	global_load_dword v242, v243, s[0:1] offset:3584
	s_add_u32 s0, s0, 0x1e00
	s_addc_u32 s1, s1, 0
	global_load_dword v242, v243, s[0:1] offset:1536
	global_load_dword v242, v243, s[0:1] offset:2560
	global_load_dword v242, v243, s[0:1] offset:3584
	s_add_u32 s0, s0, 0x1e00
	s_addc_u32 s1, s1, 0
	global_load_dword v242, v243, s[0:1] offset:1536
	global_load_dword v242, v243, s[0:1] offset:2560
	global_load_dword v242, v243, s[0:1] offset:3584
	s_add_u32 s0, s0, 0x1e00
	s_addc_u32 s1, s1, 0
	global_load_dword v242, v243, s[0:1] offset:1536
	global_load_dword v242, v243, s[0:1] offset:2560
	global_load_dword v242, v243, s[0:1] offset:3584
	s_add_u32 s0, s0, 0x1e00
	s_addc_u32 s1, s1, 0
	global_load_dword v242, v243, s[0:1] offset:1536
	global_load_dword v242, v243, s[0:1] offset:2560
	global_load_dword v242, v243, s[0:1] offset:3584
	s_add_u32 s0, s0, 0x1e00
	s_addc_u32 s1, s1, 0
	global_load_dword v242, v243, s[0:1] offset:1536
	global_load_dword v242, v243, s[0:1] offset:2560
	global_load_dword v242, v243, s[0:1] offset:3584
	s_add_u32 s0, s0, 0x1e00
	s_addc_u32 s1, s1, 0
	global_load_dword v242, v243, s[0:1] offset:1536
	global_load_dword v242, v243, s[0:1] offset:2560
	global_load_dword v242, v243, s[0:1] offset:3584
	s_add_u32 s0, s0, 0x1e00
	s_addc_u32 s1, s1, 0
	global_load_dword v242, v243, s[0:1] offset:1536
	global_load_dword v242, v243, s[0:1] offset:2560
	global_load_dword v242, v243, s[0:1] offset:3584
	s_add_u32 s0, s0, 0x1e00
	s_addc_u32 s1, s1, 0
	global_load_dword v242, v243, s[0:1] offset:1536
	global_load_dword v242, v243, s[0:1] offset:2560
	global_load_dword v242, v243, s[0:1] offset:3584
	s_add_u32 s0, s0, 0x1e00
	s_addc_u32 s1, s1, 0
	global_load_dword v242, v243, s[0:1] offset:1536
	global_load_dword v242, v243, s[0:1] offset:2560
	global_load_dword v242, v243, s[0:1] offset:3584
.Lprep_pf_skip:
	s_mov_b64 s[0:1], -1
	s_and_b64 vcc, exec, s[60:61]
	s_cbranch_vccz .LBB0_560
	s_mov_b64 s[0:1], exec
	v_readlane_b32 s16, v254, 28
	v_readlane_b32 s17, v254, 29
	s_and_b64 s[16:17], s[0:1], s[16:17]
	s_mov_b64 exec, s[16:17]
	s_cbranch_execz .LBB0_547
	s_lshl_b32 s16, s53, 1
	v_readlane_b32 s18, v250, 61
	v_readlane_b32 s19, v250, 62
	s_add_u32 s16, s18, s16
	s_addc_u32 s17, s19, 0
	s_mov_b64 s[18:19], 0
	v_mov_b32_e32 v4, v101
	v_mov_b32_e32 v5, v100
